# v54 + O-rescale in SEL/WIN/MLA tile loops uses 64 v_mul_f32 instead of 32 v_pk_mul_f32
# baseline (speedup 1.0000x reference)
; __device__ __forceinline__ float xhalf_max(float x) { const auto r = __builtin_amdgcn_permlane32_swap(__float_as_uint(x), __float_as_uint(x), false, false); return fmaxf(__uint_as_float(r[0]), __uint_as_float(r[1])); }
; __device__ __forceinline__ float xhalf_sum(float x) { const auto r = __builtin_amdgcn_permlane32_swap(__float_as_uint(x), __float_as_uint(x), false, false); return __uint_as_float(r[0]) + __uint_as_float(r[1]); }
; template <int MODE, int NQ> ...
;     ...
;                 float mx = s0[0];
; #pragma unroll
;                 for (int r = 1; r < 16; ++r) mx = fmaxf(mx, s0[r]);
; #pragma unroll
;                 for (int r = 0; r < 16; ++r) mx = fmaxf(mx, s1[r]);
;                 mx = xhalf_max(mx);
;                 if (MODE == M_SEL) mx = lv ? mx : -__builtin_inff();
;                 const float mn = fmaxf(m, mx * C), alpha = __builtin_amdgcn_exp2f(m - mn);
;                 m = mn;
;                 float rs = 0.f;
; #pragma unroll
;                 for (int r = 0; r < 16; ++r) { s0[r] = __builtin_amdgcn_exp2f(s0[r] * C - mn); s1[r] = __builtin_amdgcn_exp2f(s1[r] * C - mn); rs += s0[r] + s1[r]; }
;                 rs = xhalf_sum(rs);
;                 if (MODE == M_SEL) rs = lv ? rs : 0.f;
;                 l = l * alpha + rs;
;                 if (MODE != M_CMP1) {
;                     if (!__all(alpha == 1.0f)) {
; #pragma unroll
;                         for (int db = 0; db < 4; ++db)
; #pragma unroll
;                             for (int r = 0; r < 16; ++r) O[db][r] *= alpha;
;                     }
.LBB0_926:
	s_nop 8
	v_max_f32_e32 v163, v67, v67
	v_max_f32_e32 v172, v66, v66
	v_max_f32_e32 v163, v172, v163
	v_max3_f32 v163, v163, v68, v69
	v_max3_f32 v163, v163, v70, v71
	v_max3_f32 v163, v163, v72, v73
	v_max3_f32 v163, v163, v74, v75
	v_max3_f32 v163, v163, v76, v77
	v_max3_f32 v163, v163, v78, v79
	v_max3_f32 v163, v163, v80, v81
	v_max3_f32 v163, v163, v82, v83
	v_max3_f32 v163, v163, v84, v85
	v_max3_f32 v163, v163, v86, v87
	v_max3_f32 v163, v163, v88, v89
	v_max3_f32 v163, v163, v90, v91
	v_max3_f32 v163, v163, v92, v93
	v_max3_f32 v163, v163, v94, v95
	v_max3_f32 v163, v163, v96, v97
	v_mov_b32_e32 v172, v163
	s_nop 1
	v_permlane32_swap_b32_e32 v163, v172
	v_max_f32_e32 v172, v172, v172
	v_max_f32_e32 v163, v163, v163
	v_max_f32_e32 v163, v163, v172
	v_mul_f32_e32 v163, 0x3e0293ee, v163
	v_cndmask_b32_e64 v163, v1, v163, s[2:3]
	v_max_f32_e32 v172, v211, v211
	v_max_f32_e32 v163, v172, v163
	v_fma_f32 v68, v68, s76, -v163
	v_exp_f32_e32 v177, v68
	v_fma_f32 v68, v84, s76, -v163
	v_fma_f32 v66, v66, s76, -v163
	v_exp_f32_e32 v84, v68
	v_fma_f32 v68, v69, s76, -v163
	v_fma_f32 v69, v70, s76, -v163
	v_exp_f32_e32 v175, v66
	v_fma_f32 v66, v82, s76, -v163
	v_exp_f32_e32 v179, v69
	v_fma_f32 v69, v86, s76, -v163
	v_exp_f32_e32 v82, v66
	v_fma_f32 v66, v67, s76, -v163
	v_exp_f32_e32 v86, v69
	v_fma_f32 v69, v71, s76, -v163
	v_exp_f32_e32 v176, v66
	v_fma_f32 v66, v83, s76, -v163
	v_exp_f32_e32 v180, v69
	v_fma_f32 v69, v87, s76, -v163
	v_exp_f32_e32 v83, v66
	v_exp_f32_e32 v87, v69
	v_fma_f32 v69, v72, s76, -v163
	v_exp_f32_e32 v181, v69
	v_fma_f32 v69, v88, s76, -v163
	v_exp_f32_e32 v88, v69
	v_fma_f32 v69, v73, s76, -v163
	v_add_f32_e32 v67, v175, v82
	v_exp_f32_e32 v182, v69
	v_fma_f32 v69, v89, s76, -v163
	v_add_f32_e32 v67, 0, v67
	v_add_f32_e32 v172, v176, v83
	v_exp_f32_e32 v89, v69
	v_fma_f32 v69, v74, s76, -v163
	v_exp_f32_e32 v178, v68
	v_fma_f32 v68, v85, s76, -v163
	v_add_f32_e32 v67, v172, v67
	v_exp_f32_e32 v172, v69
	v_fma_f32 v69, v90, s76, -v163
	v_exp_f32_e32 v85, v68
	v_exp_f32_e32 v90, v69
	v_fma_f32 v69, v75, s76, -v163
	v_exp_f32_e32 v173, v69
	v_fma_f32 v69, v91, s76, -v163
	v_exp_f32_e32 v91, v69
	v_fma_f32 v69, v76, s76, -v163
	v_add_f32_e32 v68, v177, v84
	v_exp_f32_e32 v174, v69
	v_fma_f32 v69, v92, s76, -v163
	v_add_f32_e32 v67, v68, v67
	v_add_f32_e32 v68, v178, v85
	v_exp_f32_e32 v71, v69
	v_fma_f32 v69, v77, s76, -v163
	v_add_f32_e32 v67, v68, v67
	v_add_f32_e32 v68, v179, v86
	v_exp_f32_e32 v92, v69
	v_fma_f32 v69, v93, s76, -v163
	v_add_f32_e32 v67, v68, v67
	v_add_f32_e32 v68, v180, v87
	v_exp_f32_e32 v72, v69
	v_fma_f32 v69, v78, s76, -v163
	v_add_f32_e32 v67, v68, v67
	v_add_f32_e32 v68, v181, v88
	v_exp_f32_e32 v93, v69
	v_fma_f32 v69, v94, s76, -v163
	v_add_f32_e32 v67, v68, v67
	v_add_f32_e32 v68, v182, v89
	v_exp_f32_e32 v73, v69
	v_fma_f32 v69, v79, s76, -v163
	v_add_f32_e32 v67, v68, v67
	v_add_f32_e32 v68, v172, v90
	v_exp_f32_e32 v79, v69
	v_fma_f32 v69, v95, s76, -v163
	v_add_f32_e32 v67, v68, v67
	v_add_f32_e32 v68, v173, v91
	v_exp_f32_e32 v74, v69
	v_add_f32_e32 v67, v68, v67
	v_add_f32_e32 v68, v174, v71
	v_add_f32_e32 v67, v68, v67
	v_add_f32_e32 v68, v92, v72
	v_add_f32_e32 v67, v68, v67
	v_add_f32_e32 v68, v93, v73
	v_add_f32_e32 v67, v68, v67
	v_add_f32_e32 v68, v79, v74
	v_add_f32_e32 v67, v68, v67
	v_fma_f32 v68, v80, s76, -v163
	v_exp_f32_e32 v80, v68
	v_fma_f32 v68, v96, s76, -v163
	v_exp_f32_e32 v75, v68
	v_fma_f32 v68, v81, s76, -v163
	v_exp_f32_e32 v81, v68
	v_fma_f32 v68, v97, s76, -v163
	v_exp_f32_e32 v76, v68
	v_sub_f32_e32 v66, v211, v163
	v_exp_f32_e32 v70, v66
	v_add_f32_e32 v68, v80, v75
	v_add_f32_e32 v67, v68, v67
	v_add_f32_e32 v66, v81, v76
	v_add_f32_e32 v77, v66, v67
	v_mov_b32_e32 v78, v77
	v_cmp_eq_f32_e32 vcc, 1.0, v70
	s_cmp_eq_u64 vcc, exec
	v_permlane32_swap_b32_e32 v77, v78
	s_cbranch_scc1 .LBB0_928
	v_mul_f32_e32 v64, v70, v64
	v_mul_f32_e32 v65, v70, v65
	v_mul_f32_e32 v62, v70, v62
	v_mul_f32_e32 v63, v70, v63
	v_mul_f32_e32 v60, v70, v60
	v_mul_f32_e32 v61, v70, v61
	v_mul_f32_e32 v58, v70, v58
	v_mul_f32_e32 v59, v70, v59
	v_mul_f32_e32 v56, v70, v56
	v_mul_f32_e32 v57, v70, v57
	v_mul_f32_e32 v54, v70, v54
	v_mul_f32_e32 v55, v70, v55
	v_mul_f32_e32 v52, v70, v52
	v_mul_f32_e32 v53, v70, v53
	v_mul_f32_e32 v50, v70, v50
	v_mul_f32_e32 v51, v70, v51
	v_mul_f32_e32 v48, v70, v48
	v_mul_f32_e32 v49, v70, v49
	v_mul_f32_e32 v46, v70, v46
	v_mul_f32_e32 v47, v70, v47
	v_mul_f32_e32 v44, v70, v44
	v_mul_f32_e32 v45, v70, v45
	v_mul_f32_e32 v42, v70, v42
	v_mul_f32_e32 v43, v70, v43
	v_mul_f32_e32 v40, v70, v40
	v_mul_f32_e32 v41, v70, v41
	v_mul_f32_e32 v38, v70, v38
	v_mul_f32_e32 v39, v70, v39
	v_mul_f32_e32 v36, v70, v36
	v_mul_f32_e32 v37, v70, v37
	v_mul_f32_e32 v34, v70, v34
	v_mul_f32_e32 v35, v70, v35
	v_mul_f32_e32 v32, v70, v32
	v_mul_f32_e32 v33, v70, v33
	v_mul_f32_e32 v30, v70, v30
	v_mul_f32_e32 v31, v70, v31
	v_mul_f32_e32 v28, v70, v28
	v_mul_f32_e32 v29, v70, v29
	v_mul_f32_e32 v26, v70, v26
	v_mul_f32_e32 v27, v70, v27
	v_mul_f32_e32 v24, v70, v24
	v_mul_f32_e32 v25, v70, v25
	v_mul_f32_e32 v22, v70, v22
	v_mul_f32_e32 v23, v70, v23
	v_mul_f32_e32 v20, v70, v20
	v_mul_f32_e32 v21, v70, v21
	v_mul_f32_e32 v18, v70, v18
	v_mul_f32_e32 v19, v70, v19
	v_mul_f32_e32 v16, v70, v16
	v_mul_f32_e32 v17, v70, v17
	v_mul_f32_e32 v14, v70, v14
	v_mul_f32_e32 v15, v70, v15
	v_mul_f32_e32 v12, v70, v12
	v_mul_f32_e32 v13, v70, v13
	v_mul_f32_e32 v10, v70, v10
	v_mul_f32_e32 v11, v70, v11
	v_mul_f32_e32 v8, v70, v8
	v_mul_f32_e32 v9, v70, v9
	v_mul_f32_e32 v6, v70, v6
	v_mul_f32_e32 v7, v70, v7
	v_mul_f32_e32 v4, v70, v4
	v_mul_f32_e32 v5, v70, v5
	v_mul_f32_e32 v2, v70, v2
	v_mul_f32_e32 v3, v70, v3

; __device__ __forceinline__ float xhalf_max(float x) { const auto r = __builtin_amdgcn_permlane32_swap(__float_as_uint(x), __float_as_uint(x), false, false); return fmaxf(__uint_as_float(r[0]), __uint_as_float(r[1])); }
; __device__ __forceinline__ float xhalf_sum(float x) { const auto r = __builtin_amdgcn_permlane32_swap(__float_as_uint(x), __float_as_uint(x), false, false); return __uint_as_float(r[0]) + __uint_as_float(r[1]); }
; template <int MODE, int NQ> ...
;     ...
;                 float mx = s0[0];
; #pragma unroll
;                 for (int r = 1; r < 16; ++r) mx = fmaxf(mx, s0[r]);
; #pragma unroll
;                 for (int r = 0; r < 16; ++r) mx = fmaxf(mx, s1[r]);
;                 mx = xhalf_max(mx);
;                 if (MODE == M_SEL) mx = lv ? mx : -__builtin_inff();
;                 const float mn = fmaxf(m, mx * C), alpha = __builtin_amdgcn_exp2f(m - mn);
;                 m = mn;
;                 float rs = 0.f;
; #pragma unroll
;                 for (int r = 0; r < 16; ++r) { s0[r] = __builtin_amdgcn_exp2f(s0[r] * C - mn); s1[r] = __builtin_amdgcn_exp2f(s1[r] * C - mn); rs += s0[r] + s1[r]; }
;                 rs = xhalf_sum(rs);
;                 if (MODE == M_SEL) rs = lv ? rs : 0.f;
;                 l = l * alpha + rs;
;                 if (MODE != M_CMP1) {
;                     if (!__all(alpha == 1.0f)) {
; #pragma unroll
;                         for (int db = 0; db < 4; ++db)
; #pragma unroll
;                             for (int r = 0; r < 16; ++r) O[db][r] *= alpha;
;                     }
.LBB0_941:
	s_nop 8
	v_max_f32_e32 v167, v67, v67
	v_max_f32_e32 v169, v66, v66
	v_max_f32_e32 v167, v169, v167
	v_max3_f32 v167, v167, v68, v69
	v_max3_f32 v167, v167, v70, v71
	v_max3_f32 v167, v167, v72, v73
	v_max3_f32 v167, v167, v74, v75
	v_max3_f32 v167, v167, v76, v77
	v_max3_f32 v167, v167, v78, v79
	v_max3_f32 v167, v167, v80, v81
	v_max3_f32 v167, v167, v82, v83
	v_max3_f32 v167, v167, v84, v85
	v_max3_f32 v167, v167, v86, v87
	v_max3_f32 v167, v167, v88, v89
	v_max3_f32 v167, v167, v90, v91
	v_max3_f32 v167, v167, v92, v93
	v_max3_f32 v167, v167, v94, v95
	v_max3_f32 v167, v167, v96, v97
	v_mov_b32_e32 v169, v167
	s_nop 1
	v_permlane32_swap_b32_e32 v167, v169
	v_max_f32_e32 v169, v169, v169
	v_max_f32_e32 v167, v167, v167
	v_max_f32_e32 v167, v167, v169
	v_mul_f32_e32 v167, 0x3e0293ee, v167
	v_max_f32_e32 v169, v168, v168
	v_max_f32_e32 v167, v169, v167
	v_fma_f32 v66, v66, s76, -v167
	v_exp_f32_e32 v169, v66
	v_fma_f32 v66, v82, s76, -v167
	v_exp_f32_e32 v82, v66
	v_fma_f32 v66, v67, s76, -v167
	v_exp_f32_e32 v171, v66
	v_fma_f32 v66, v83, s76, -v167
	v_fma_f32 v68, v68, s76, -v167
	v_exp_f32_e32 v67, v66
	v_exp_f32_e32 v173, v68
	v_fma_f32 v68, v84, s76, -v167
	v_exp_f32_e32 v68, v68
	v_fma_f32 v69, v69, s76, -v167
	v_add_f32_e32 v83, v169, v82
	v_exp_f32_e32 v175, v69
	v_fma_f32 v69, v85, s76, -v167
	v_sub_f32_e32 v66, v168, v167
	v_add_f32_e32 v168, 0, v83
	v_exp_f32_e32 v83, v69
	v_add_f32_e32 v170, v171, v67
	v_fma_f32 v70, v70, s76, -v167
	v_add_f32_e32 v69, v170, v168
	v_add_f32_e32 v84, v173, v68
	v_exp_f32_e32 v168, v70
	v_fma_f32 v70, v86, s76, -v167
	v_add_f32_e32 v69, v84, v69
	v_exp_f32_e32 v84, v70
	v_fma_f32 v70, v71, s76, -v167
	v_add_f32_e32 v172, v175, v83
	v_exp_f32_e32 v170, v70
	v_fma_f32 v70, v87, s76, -v167
	v_fma_f32 v71, v72, s76, -v167
	v_exp_f32_e32 v85, v70
	v_add_f32_e32 v69, v172, v69
	v_exp_f32_e32 v172, v71
	v_fma_f32 v71, v88, s76, -v167
	v_exp_f32_e32 v72, v71
	v_add_f32_e32 v70, v168, v84
	v_add_f32_e32 v69, v70, v69
	v_add_f32_e32 v70, v170, v85
	v_fma_f32 v71, v73, s76, -v167
	v_exp_f32_e32 v174, v71
	v_fma_f32 v71, v89, s76, -v167
	v_add_f32_e32 v69, v70, v69
	v_add_f32_e32 v70, v172, v72
	v_exp_f32_e32 v86, v71
	v_add_f32_e32 v71, v70, v69
	v_fma_f32 v69, v74, s76, -v167
	v_exp_f32_e32 v87, v69
	v_fma_f32 v69, v90, s76, -v167
	v_exp_f32_e32 v69, v69
	v_add_f32_e32 v73, v174, v86
	v_fma_f32 v70, v75, s76, -v167
	v_add_f32_e32 v71, v73, v71
	v_add_f32_e32 v73, v87, v69
	v_exp_f32_e32 v88, v70
	v_fma_f32 v70, v91, s76, -v167
	v_add_f32_e32 v73, v73, v71
	v_fma_f32 v71, v76, s76, -v167
	v_exp_f32_e32 v70, v70
	v_exp_f32_e32 v89, v71
	v_fma_f32 v71, v92, s76, -v167
	v_fma_f32 v75, v77, s76, -v167
	v_exp_f32_e32 v71, v71
	v_exp_f32_e32 v90, v75
	v_fma_f32 v75, v93, s76, -v167
	v_fma_f32 v76, v78, s76, -v167
	v_exp_f32_e32 v75, v75
	v_exp_f32_e32 v91, v76
	v_fma_f32 v76, v94, s76, -v167
	v_fma_f32 v77, v79, s76, -v167
	v_exp_f32_e32 v76, v76
	v_exp_f32_e32 v92, v77
	v_fma_f32 v77, v95, s76, -v167
	v_add_f32_e32 v74, v88, v70
	v_exp_f32_e32 v78, v77
	v_add_f32_e32 v73, v74, v73
	v_add_f32_e32 v74, v89, v71
	v_add_f32_e32 v73, v74, v73
	v_add_f32_e32 v74, v90, v75
	v_add_f32_e32 v73, v74, v73
	v_add_f32_e32 v74, v91, v76
	v_add_f32_e32 v73, v74, v73
	v_add_f32_e32 v74, v92, v78
	v_add_f32_e32 v73, v74, v73
	v_fma_f32 v74, v80, s76, -v167
	v_exp_f32_e32 v80, v74
	v_fma_f32 v74, v96, s76, -v167
	v_exp_f32_e32 v77, v74
	v_fma_f32 v74, v81, s76, -v167
	v_exp_f32_e32 v81, v74
	v_fma_f32 v74, v97, s76, -v167
	v_exp_f32_e32 v79, v74
	v_exp_f32_e32 v66, v66
	v_add_f32_e32 v74, v80, v77
	v_add_f32_e32 v73, v74, v73
	v_add_f32_e32 v74, v81, v79
	v_add_f32_e32 v73, v74, v73
	v_mov_b32_e32 v74, v73
	v_cmp_eq_f32_e32 vcc, 1.0, v66
	s_cmp_eq_u64 vcc, exec
	v_permlane32_swap_b32_e32 v73, v74
	s_cbranch_scc1 .LBB0_943
	v_mul_f32_e32 v64, v66, v64
	v_mul_f32_e32 v65, v66, v65
	v_mul_f32_e32 v62, v66, v62
	v_mul_f32_e32 v63, v66, v63
	v_mul_f32_e32 v60, v66, v60
	v_mul_f32_e32 v61, v66, v61
	v_mul_f32_e32 v58, v66, v58
	v_mul_f32_e32 v59, v66, v59
	v_mul_f32_e32 v56, v66, v56
	v_mul_f32_e32 v57, v66, v57
	v_mul_f32_e32 v54, v66, v54
	v_mul_f32_e32 v55, v66, v55
	v_mul_f32_e32 v52, v66, v52
	v_mul_f32_e32 v53, v66, v53
	v_mul_f32_e32 v50, v66, v50
	v_mul_f32_e32 v51, v66, v51
	v_mul_f32_e32 v48, v66, v48
	v_mul_f32_e32 v49, v66, v49
	v_mul_f32_e32 v46, v66, v46
	v_mul_f32_e32 v47, v66, v47
	v_mul_f32_e32 v44, v66, v44
	v_mul_f32_e32 v45, v66, v45
	v_mul_f32_e32 v42, v66, v42
	v_mul_f32_e32 v43, v66, v43
	v_mul_f32_e32 v40, v66, v40
	v_mul_f32_e32 v41, v66, v41
	v_mul_f32_e32 v38, v66, v38
	v_mul_f32_e32 v39, v66, v39
	v_mul_f32_e32 v36, v66, v36
	v_mul_f32_e32 v37, v66, v37
	v_mul_f32_e32 v34, v66, v34
	v_mul_f32_e32 v35, v66, v35
	v_mul_f32_e32 v32, v66, v32
	v_mul_f32_e32 v33, v66, v33
	v_mul_f32_e32 v30, v66, v30
	v_mul_f32_e32 v31, v66, v31
	v_mul_f32_e32 v28, v66, v28
	v_mul_f32_e32 v29, v66, v29
	v_mul_f32_e32 v26, v66, v26
	v_mul_f32_e32 v27, v66, v27
	v_mul_f32_e32 v24, v66, v24
	v_mul_f32_e32 v25, v66, v25
	v_mul_f32_e32 v22, v66, v22
	v_mul_f32_e32 v23, v66, v23
	v_mul_f32_e32 v20, v66, v20
	v_mul_f32_e32 v21, v66, v21
	v_mul_f32_e32 v18, v66, v18
	v_mul_f32_e32 v19, v66, v19
	v_mul_f32_e32 v16, v66, v16
	v_mul_f32_e32 v17, v66, v17
	v_mul_f32_e32 v14, v66, v14
	v_mul_f32_e32 v15, v66, v15
	v_mul_f32_e32 v12, v66, v12
	v_mul_f32_e32 v13, v66, v13
	v_mul_f32_e32 v10, v66, v10
	v_mul_f32_e32 v11, v66, v11
	v_mul_f32_e32 v8, v66, v8
	v_mul_f32_e32 v9, v66, v9
	v_mul_f32_e32 v6, v66, v6
	v_mul_f32_e32 v7, v66, v7
	v_mul_f32_e32 v4, v66, v4
	v_mul_f32_e32 v5, v66, v5
	v_mul_f32_e32 v2, v66, v2
	v_mul_f32_e32 v3, v66, v3

; __device__ __forceinline__ float xhalf_max(float x) { const auto r = __builtin_amdgcn_permlane32_swap(__float_as_uint(x), __float_as_uint(x), false, false); return fmaxf(__uint_as_float(r[0]), __uint_as_float(r[1])); }
; __device__ __forceinline__ float xhalf_sum(float x) { const auto r = __builtin_amdgcn_permlane32_swap(__float_as_uint(x), __float_as_uint(x), false, false); return __uint_as_float(r[0]) + __uint_as_float(r[1]); }
; template <int MODE, int NQ> ...
;     ...
;                 float mx = s0[0];
; #pragma unroll
;                 for (int r = 1; r < 16; ++r) mx = fmaxf(mx, s0[r]);
; #pragma unroll
;                 for (int r = 0; r < 16; ++r) mx = fmaxf(mx, s1[r]);
;                 mx = xhalf_max(mx);
;                 if (MODE == M_SEL) mx = lv ? mx : -__builtin_inff();
;                 const float mn = fmaxf(m, mx * C), alpha = __builtin_amdgcn_exp2f(m - mn);
;                 m = mn;
;                 float rs = 0.f;
; #pragma unroll
;                 for (int r = 0; r < 16; ++r) { s0[r] = __builtin_amdgcn_exp2f(s0[r] * C - mn); s1[r] = __builtin_amdgcn_exp2f(s1[r] * C - mn); rs += s0[r] + s1[r]; }
;                 rs = xhalf_sum(rs);
;                 if (MODE == M_SEL) rs = lv ? rs : 0.f;
;                 l = l * alpha + rs;
;                 if (MODE != M_CMP1) {
;                     if (!__all(alpha == 1.0f)) {
; #pragma unroll
;                         for (int db = 0; db < 4; ++db)
; #pragma unroll
;                             for (int r = 0; r < 16; ++r) O[db][r] *= alpha;
;                     }
.LBB0_967:
	s_nop 8
	v_max_f32_e32 v189, v67, v67
	v_max_f32_e32 v191, v66, v66
	v_max_f32_e32 v189, v191, v189
	v_max3_f32 v189, v189, v68, v69
	v_max3_f32 v189, v189, v70, v71
	v_max3_f32 v189, v189, v72, v73
	v_max3_f32 v189, v189, v74, v75
	v_max3_f32 v189, v189, v76, v77
	v_max3_f32 v189, v189, v78, v79
	v_max3_f32 v189, v189, v80, v81
	v_max3_f32 v189, v189, v82, v83
	v_max3_f32 v189, v189, v84, v85
	v_max3_f32 v189, v189, v86, v87
	v_max3_f32 v189, v189, v88, v89
	v_max3_f32 v189, v189, v90, v91
	v_max3_f32 v189, v189, v92, v93
	v_max3_f32 v189, v189, v94, v95
	v_max3_f32 v189, v189, v96, v97
	v_mov_b32_e32 v191, v189
	s_nop 1
	v_permlane32_swap_b32_e32 v189, v191
	v_max_f32_e32 v191, v191, v191
	v_max_f32_e32 v189, v189, v189
	v_max_f32_e32 v189, v189, v191
	v_mul_f32_e32 v189, 0x3dd53b94, v189
	v_max_f32_e32 v191, v190, v190
	v_max_f32_e32 v189, v191, v189
	v_fma_f32 v66, v66, s77, -v189
	v_exp_f32_e32 v191, v66
	v_fma_f32 v66, v82, s77, -v189
	v_exp_f32_e32 v82, v66
	v_fma_f32 v66, v67, s77, -v189
	v_exp_f32_e32 v193, v66
	v_fma_f32 v66, v83, s77, -v189
	v_fma_f32 v68, v68, s77, -v189
	v_exp_f32_e32 v67, v66
	v_exp_f32_e32 v195, v68
	v_fma_f32 v68, v84, s77, -v189
	v_exp_f32_e32 v68, v68
	v_fma_f32 v69, v69, s77, -v189
	v_add_f32_e32 v83, v191, v82
	v_exp_f32_e32 v197, v69
	v_fma_f32 v69, v85, s77, -v189
	v_sub_f32_e32 v66, v190, v189
	v_add_f32_e32 v190, 0, v83
	v_exp_f32_e32 v83, v69
	v_add_f32_e32 v192, v193, v67
	v_fma_f32 v70, v70, s77, -v189
	v_add_f32_e32 v69, v192, v190
	v_add_f32_e32 v84, v195, v68
	v_exp_f32_e32 v190, v70
	v_fma_f32 v70, v86, s77, -v189
	v_add_f32_e32 v69, v84, v69
	v_exp_f32_e32 v84, v70
	v_fma_f32 v70, v71, s77, -v189
	v_add_f32_e32 v194, v197, v83
	v_exp_f32_e32 v192, v70
	v_fma_f32 v70, v87, s77, -v189
	v_fma_f32 v71, v72, s77, -v189
	v_exp_f32_e32 v85, v70
	v_add_f32_e32 v69, v194, v69
	v_exp_f32_e32 v194, v71
	v_fma_f32 v71, v88, s77, -v189
	v_exp_f32_e32 v72, v71
	v_add_f32_e32 v70, v190, v84
	v_add_f32_e32 v69, v70, v69
	v_add_f32_e32 v70, v192, v85
	v_fma_f32 v71, v73, s77, -v189
	v_exp_f32_e32 v196, v71
	v_fma_f32 v71, v89, s77, -v189
	v_add_f32_e32 v69, v70, v69
	v_add_f32_e32 v70, v194, v72
	v_exp_f32_e32 v86, v71
	v_add_f32_e32 v71, v70, v69
	v_fma_f32 v69, v74, s77, -v189
	v_exp_f32_e32 v87, v69
	v_fma_f32 v69, v90, s77, -v189
	v_exp_f32_e32 v69, v69
	v_add_f32_e32 v73, v196, v86
	v_fma_f32 v70, v75, s77, -v189
	v_add_f32_e32 v71, v73, v71
	v_add_f32_e32 v73, v87, v69
	v_exp_f32_e32 v88, v70
	v_fma_f32 v70, v91, s77, -v189
	v_add_f32_e32 v73, v73, v71
	v_fma_f32 v71, v76, s77, -v189
	v_exp_f32_e32 v70, v70
	v_exp_f32_e32 v89, v71
	v_fma_f32 v71, v92, s77, -v189
	v_fma_f32 v75, v77, s77, -v189
	v_exp_f32_e32 v71, v71
	v_exp_f32_e32 v90, v75
	v_fma_f32 v75, v93, s77, -v189
	v_fma_f32 v76, v78, s77, -v189
	v_exp_f32_e32 v75, v75
	v_exp_f32_e32 v91, v76
	v_fma_f32 v76, v94, s77, -v189
	v_fma_f32 v77, v79, s77, -v189
	v_exp_f32_e32 v76, v76
	v_exp_f32_e32 v92, v77
	v_fma_f32 v77, v95, s77, -v189
	v_add_f32_e32 v74, v88, v70
	v_exp_f32_e32 v78, v77
	v_add_f32_e32 v73, v74, v73
	v_add_f32_e32 v74, v89, v71
	v_add_f32_e32 v73, v74, v73
	v_add_f32_e32 v74, v90, v75
	v_add_f32_e32 v73, v74, v73
	v_add_f32_e32 v74, v91, v76
	v_add_f32_e32 v73, v74, v73
	v_add_f32_e32 v74, v92, v78
	v_add_f32_e32 v73, v74, v73
	v_fma_f32 v74, v80, s77, -v189
	v_exp_f32_e32 v80, v74
	v_fma_f32 v74, v96, s77, -v189
	v_exp_f32_e32 v77, v74
	v_fma_f32 v74, v81, s77, -v189
	v_exp_f32_e32 v81, v74
	v_fma_f32 v74, v97, s77, -v189
	v_exp_f32_e32 v79, v74
	v_exp_f32_e32 v66, v66
	v_add_f32_e32 v74, v80, v77
	v_add_f32_e32 v73, v74, v73
	v_add_f32_e32 v74, v81, v79
	v_add_f32_e32 v73, v74, v73
	v_mov_b32_e32 v74, v73
	v_cmp_eq_f32_e32 vcc, 1.0, v66
	s_cmp_eq_u64 vcc, exec
	v_permlane32_swap_b32_e32 v73, v74
	s_cbranch_scc1 .LBB0_969
	v_mul_f32_e32 v64, v66, v64
	v_mul_f32_e32 v65, v66, v65
	v_mul_f32_e32 v62, v66, v62
	v_mul_f32_e32 v63, v66, v63
	v_mul_f32_e32 v60, v66, v60
	v_mul_f32_e32 v61, v66, v61
	v_mul_f32_e32 v58, v66, v58
	v_mul_f32_e32 v59, v66, v59
	v_mul_f32_e32 v56, v66, v56
	v_mul_f32_e32 v57, v66, v57
	v_mul_f32_e32 v54, v66, v54
	v_mul_f32_e32 v55, v66, v55
	v_mul_f32_e32 v52, v66, v52
	v_mul_f32_e32 v53, v66, v53
	v_mul_f32_e32 v50, v66, v50
	v_mul_f32_e32 v51, v66, v51
	v_mul_f32_e32 v48, v66, v48
	v_mul_f32_e32 v49, v66, v49
	v_mul_f32_e32 v46, v66, v46
	v_mul_f32_e32 v47, v66, v47
	v_mul_f32_e32 v44, v66, v44
	v_mul_f32_e32 v45, v66, v45
	v_mul_f32_e32 v42, v66, v42
	v_mul_f32_e32 v43, v66, v43
	v_mul_f32_e32 v40, v66, v40
	v_mul_f32_e32 v41, v66, v41
	v_mul_f32_e32 v38, v66, v38
	v_mul_f32_e32 v39, v66, v39
	v_mul_f32_e32 v36, v66, v36
	v_mul_f32_e32 v37, v66, v37
	v_mul_f32_e32 v34, v66, v34
	v_mul_f32_e32 v35, v66, v35
	v_mul_f32_e32 v32, v66, v32
	v_mul_f32_e32 v33, v66, v33
	v_mul_f32_e32 v30, v66, v30
	v_mul_f32_e32 v31, v66, v31
	v_mul_f32_e32 v28, v66, v28
	v_mul_f32_e32 v29, v66, v29
	v_mul_f32_e32 v26, v66, v26
	v_mul_f32_e32 v27, v66, v27
	v_mul_f32_e32 v24, v66, v24
	v_mul_f32_e32 v25, v66, v25
	v_mul_f32_e32 v22, v66, v22
	v_mul_f32_e32 v23, v66, v23
	v_mul_f32_e32 v20, v66, v20
	v_mul_f32_e32 v21, v66, v21
	v_mul_f32_e32 v18, v66, v18
	v_mul_f32_e32 v19, v66, v19
	v_mul_f32_e32 v16, v66, v16
	v_mul_f32_e32 v17, v66, v17
	v_mul_f32_e32 v14, v66, v14
	v_mul_f32_e32 v15, v66, v15
	v_mul_f32_e32 v12, v66, v12
	v_mul_f32_e32 v13, v66, v13
	v_mul_f32_e32 v10, v66, v10
	v_mul_f32_e32 v11, v66, v11
	v_mul_f32_e32 v8, v66, v8
	v_mul_f32_e32 v9, v66, v9
	v_mul_f32_e32 v6, v66, v6
	v_mul_f32_e32 v7, v66, v7
	v_mul_f32_e32 v4, v66, v4
	v_mul_f32_e32 v5, v66, v5
	v_mul_f32_e32 v2, v66, v2
	v_mul_f32_e32 v3, v66, v3
